# baseline (speedup 1.0000x reference)
.LBB0_30:
	buffer_wbl2 sc1
	v_mov_b64 v[0:1], 0
	v_mov_b64 v[2:3], 0
	v_mov_b64 v[4:5], 0
	v_mov_b64 v[6:7], 0
	v_mov_b64 v[8:9], 0
	v_mov_b64 v[10:11], 0
	v_mov_b64 v[12:13], 0
	v_mov_b64 v[14:15], 0
	v_mov_b64 v[16:17], 0
	v_mov_b64 v[18:19], 0
	v_mov_b64 v[20:21], 0
	v_mov_b64 v[22:23], 0
	v_mov_b64 v[24:25], 0
	v_mov_b64 v[26:27], 0
	v_mov_b64 v[28:29], 0
	v_mov_b64 v[30:31], 0
	v_mov_b64 v[32:33], 0
	v_mov_b64 v[34:35], 0
	v_mov_b64 v[36:37], 0
	v_mov_b64 v[38:39], 0
	v_mov_b64 v[40:41], 0
	v_mov_b64 v[42:43], 0
	v_mov_b64 v[44:45], 0
	v_mov_b64 v[46:47], 0
	v_mov_b64 v[48:49], 0
	v_mov_b64 v[50:51], 0
	v_mov_b64 v[52:53], 0
	v_mov_b64 v[54:55], 0
	v_mov_b64 v[56:57], 0
	v_mov_b64 v[58:59], 0
	v_mov_b64 v[60:61], 0
	v_mov_b64 v[62:63], 0
	v_mov_b64 v[64:65], 0
	v_mov_b64 v[66:67], 0
	v_mov_b64 v[68:69], 0
	v_mov_b64 v[70:71], 0
	v_mov_b64 v[72:73], 0
	v_mov_b64 v[74:75], 0
	v_mov_b64 v[76:77], 0
	v_mov_b64 v[78:79], 0
	v_mov_b64 v[80:81], 0
	v_mov_b64 v[82:83], 0
	v_mov_b64 v[84:85], 0
	v_mov_b64 v[86:87], 0
	v_mov_b64 v[88:89], 0
	v_mov_b64 v[90:91], 0
	v_mov_b64 v[92:93], 0
	v_mov_b64 v[94:95], 0
	v_mov_b64 v[96:97], 0
	v_mov_b64 v[98:99], 0
	v_mov_b64 v[100:101], 0
	v_mov_b64 v[102:103], 0
	v_mov_b64 v[104:105], 0
	v_mov_b64 v[106:107], 0
	v_mov_b64 v[108:109], 0
	v_mov_b64 v[110:111], 0
	v_mov_b64 v[112:113], 0
	v_mov_b64 v[114:115], 0
	v_mov_b64 v[116:117], 0
	v_mov_b64 v[118:119], 0
	v_mov_b64 v[120:121], 0
	v_mov_b64 v[122:123], 0
	v_mov_b64 v[124:125], 0
	v_mov_b64 v[126:127], 0
	s_and_saveexec_b64 s[36:37], s[6:7]
	s_cbranch_execz .LBB0_32
	s_barrier

.LBB0_96:
	buffer_wbl2 sc1
	v_mov_b64 v[0:1], 0
	v_mov_b64 v[2:3], 0
	v_mov_b64 v[4:5], 0
	v_mov_b64 v[6:7], 0
	v_mov_b64 v[8:9], 0
	v_mov_b64 v[10:11], 0
	v_mov_b64 v[12:13], 0
	v_mov_b64 v[14:15], 0
	v_mov_b64 v[16:17], 0
	v_mov_b64 v[18:19], 0
	v_mov_b64 v[20:21], 0
	v_mov_b64 v[22:23], 0
	v_mov_b64 v[24:25], 0
	v_mov_b64 v[26:27], 0
	v_mov_b64 v[28:29], 0
	v_mov_b64 v[30:31], 0
	v_mov_b64 v[32:33], 0
	v_mov_b64 v[34:35], 0
	v_mov_b64 v[36:37], 0
	v_mov_b64 v[38:39], 0
	v_mov_b64 v[40:41], 0
	v_mov_b64 v[42:43], 0
	v_mov_b64 v[44:45], 0
	v_mov_b64 v[46:47], 0
	v_mov_b64 v[48:49], 0
	v_mov_b64 v[50:51], 0
	v_mov_b64 v[52:53], 0
	v_mov_b64 v[54:55], 0
	v_mov_b64 v[56:57], 0
	v_mov_b64 v[58:59], 0
	v_mov_b64 v[60:61], 0
	v_mov_b64 v[62:63], 0
	v_mov_b64 v[64:65], 0
	v_mov_b64 v[66:67], 0
	v_mov_b64 v[68:69], 0
	v_mov_b64 v[70:71], 0
	v_mov_b64 v[72:73], 0
	v_mov_b64 v[74:75], 0
	v_mov_b64 v[76:77], 0
	v_mov_b64 v[78:79], 0
	v_mov_b64 v[80:81], 0
	v_mov_b64 v[82:83], 0
	v_mov_b64 v[84:85], 0
	v_mov_b64 v[86:87], 0
	v_mov_b64 v[88:89], 0
	v_mov_b64 v[90:91], 0
	v_mov_b64 v[92:93], 0
	v_mov_b64 v[94:95], 0
	v_mov_b64 v[96:97], 0
	v_mov_b64 v[98:99], 0
	v_mov_b64 v[100:101], 0
	v_mov_b64 v[102:103], 0
	v_mov_b64 v[104:105], 0
	v_mov_b64 v[106:107], 0
	v_mov_b64 v[108:109], 0
	v_mov_b64 v[110:111], 0
	v_mov_b64 v[112:113], 0
	v_mov_b64 v[114:115], 0
	v_mov_b64 v[116:117], 0
	v_mov_b64 v[118:119], 0
	v_mov_b64 v[120:121], 0
	v_mov_b64 v[122:123], 0
	v_mov_b64 v[124:125], 0
	v_mov_b64 v[126:127], 0
	s_and_saveexec_b64 s[22:23], s[6:7]
	s_cbranch_execz .LBB0_98
	s_barrier

.LBB0_132:
	buffer_wbl2 sc1
	v_mov_b64 v[0:1], 0
	v_mov_b64 v[2:3], 0
	v_mov_b64 v[4:5], 0
	v_mov_b64 v[6:7], 0
	v_mov_b64 v[8:9], 0
	v_mov_b64 v[10:11], 0
	v_mov_b64 v[12:13], 0
	v_mov_b64 v[14:15], 0
	v_mov_b64 v[16:17], 0
	v_mov_b64 v[18:19], 0
	v_mov_b64 v[20:21], 0
	v_mov_b64 v[22:23], 0
	v_mov_b64 v[24:25], 0
	v_mov_b64 v[26:27], 0
	v_mov_b64 v[28:29], 0
	v_mov_b64 v[30:31], 0
	v_mov_b64 v[32:33], 0
	v_mov_b64 v[34:35], 0
	v_mov_b64 v[36:37], 0
	v_mov_b64 v[38:39], 0
	v_mov_b64 v[40:41], 0
	v_mov_b64 v[42:43], 0
	v_mov_b64 v[44:45], 0
	v_mov_b64 v[46:47], 0
	v_mov_b64 v[48:49], 0
	v_mov_b64 v[50:51], 0
	v_mov_b64 v[52:53], 0
	v_mov_b64 v[54:55], 0
	v_mov_b64 v[56:57], 0
	v_mov_b64 v[58:59], 0
	v_mov_b64 v[60:61], 0
	v_mov_b64 v[62:63], 0
	v_mov_b64 v[64:65], 0
	v_mov_b64 v[66:67], 0
	v_mov_b64 v[68:69], 0
	v_mov_b64 v[70:71], 0
	v_mov_b64 v[72:73], 0
	v_mov_b64 v[74:75], 0
	v_mov_b64 v[76:77], 0
	v_mov_b64 v[78:79], 0
	v_mov_b64 v[80:81], 0
	v_mov_b64 v[82:83], 0
	v_mov_b64 v[84:85], 0
	v_mov_b64 v[86:87], 0
	v_mov_b64 v[88:89], 0
	v_mov_b64 v[90:91], 0
	v_mov_b64 v[92:93], 0
	v_mov_b64 v[94:95], 0
	v_mov_b64 v[96:97], 0
	v_mov_b64 v[98:99], 0
	v_mov_b64 v[100:101], 0
	v_mov_b64 v[102:103], 0
	v_mov_b64 v[104:105], 0
	v_mov_b64 v[106:107], 0
	v_mov_b64 v[108:109], 0
	v_mov_b64 v[110:111], 0
	v_mov_b64 v[112:113], 0
	v_mov_b64 v[114:115], 0
	v_mov_b64 v[116:117], 0
	v_mov_b64 v[118:119], 0
	v_mov_b64 v[120:121], 0
	v_mov_b64 v[122:123], 0
	v_mov_b64 v[124:125], 0
	v_mov_b64 v[126:127], 0
	s_mov_b32 s91, s83
	s_and_saveexec_b64 s[22:23], s[6:7]
	s_cbranch_execz .LBB0_134
	s_barrier

.LBB0_1537:
	buffer_wbl2 sc1
	v_mov_b64 v[0:1], 0
	v_mov_b64 v[2:3], 0
	v_mov_b64 v[4:5], 0
	v_mov_b64 v[6:7], 0
	v_mov_b64 v[8:9], 0
	v_mov_b64 v[10:11], 0
	v_mov_b64 v[12:13], 0
	v_mov_b64 v[14:15], 0
	v_mov_b64 v[16:17], 0
	v_mov_b64 v[18:19], 0
	v_mov_b64 v[20:21], 0
	v_mov_b64 v[22:23], 0
	v_mov_b64 v[24:25], 0
	v_mov_b64 v[26:27], 0
	v_mov_b64 v[28:29], 0
	v_mov_b64 v[30:31], 0
	v_mov_b64 v[32:33], 0
	v_mov_b64 v[34:35], 0
	v_mov_b64 v[36:37], 0
	v_mov_b64 v[38:39], 0
	v_mov_b64 v[40:41], 0
	v_mov_b64 v[42:43], 0
	v_mov_b64 v[44:45], 0
	v_mov_b64 v[46:47], 0
	v_mov_b64 v[48:49], 0
	v_mov_b64 v[50:51], 0
	v_mov_b64 v[52:53], 0
	v_mov_b64 v[54:55], 0
	v_mov_b64 v[56:57], 0
	v_mov_b64 v[58:59], 0
	v_mov_b64 v[60:61], 0
	v_mov_b64 v[62:63], 0
	v_mov_b64 v[64:65], 0
	v_mov_b64 v[66:67], 0
	v_mov_b64 v[68:69], 0
	v_mov_b64 v[70:71], 0
	v_mov_b64 v[72:73], 0
	v_mov_b64 v[74:75], 0
	v_mov_b64 v[76:77], 0
	v_mov_b64 v[78:79], 0
	v_mov_b64 v[80:81], 0
	v_mov_b64 v[82:83], 0
	v_mov_b64 v[84:85], 0
	v_mov_b64 v[86:87], 0
	v_mov_b64 v[88:89], 0
	v_mov_b64 v[90:91], 0
	v_mov_b64 v[92:93], 0
	v_mov_b64 v[94:95], 0
	v_mov_b64 v[96:97], 0
	v_mov_b64 v[98:99], 0
	v_mov_b64 v[100:101], 0
	v_mov_b64 v[102:103], 0
	v_mov_b64 v[104:105], 0
	v_mov_b64 v[106:107], 0
	v_mov_b64 v[108:109], 0
	v_mov_b64 v[110:111], 0
	v_mov_b64 v[112:113], 0
	v_mov_b64 v[114:115], 0
	v_mov_b64 v[116:117], 0
	v_mov_b64 v[118:119], 0
	v_mov_b64 v[120:121], 0
	v_mov_b64 v[122:123], 0
	v_mov_b64 v[124:125], 0
	v_mov_b64 v[126:127], 0
	s_and_saveexec_b64 s[24:25], s[6:7]
	s_cbranch_execz .LBB0_1539
	s_barrier
